# barriers 4 and 5: no L2 writeback by the XCD leaders (every store of phases 3 and 4 is write-through)
# speedup vs baseline: 1.0021x; 1.0021x over previous
.Lsplit4_nl:
.LBB0_460:
	s_andn2_saveexec_b64 s[4:5], s[4:5]
	s_cbranch_execz .LBB0_480
	s_mov_b64 s[4:5], exec
	buffer_inv sc1
	s_waitcnt lgkmcnt(0)
	s_waitcnt vmcnt(0)
	v_mbcnt_lo_u32_b32 v3, s4, 0
	v_mbcnt_hi_u32_b32 v3, s5, v3
	v_cmp_eq_u32_e32 vcc, 0, v3
	s_and_saveexec_b64 s[6:7], vcc
	s_cbranch_execz .LBB0_463
	s_bcnt1_i32_b64 s4, s[4:5]
	v_mov_b32_e32 v4, 0x7000
	v_mov_b32_e32 v5, s4
	global_atomic_add v4, v4, v5, s[82:83] offset:1024 sc0
